# nt (streaming) hint on the f32 weight loads of the P0/P4 transposes loops and on the P4 transposes stores: keeps activations cache-resident
# speedup vs baseline: 1.0196x; 1.0111x over previous
.LBB0_55:
	v_and_b32_e32 v39, 0x7c, v0
	v_add_u32_e32 v0, s2, v32
	v_ashrrev_i32_e32 v3, 31, v0
	v_mad_u64_u32 v[0:1], s[2:3], s12, v0, 0
	v_mov_b32_e32 v2, v1
	v_mad_u64_u32 v[2:3], s[2:3], s12, v3, v[2:3]
	v_or_b32_e32 v4, s14, v39
	v_mov_b32_e32 v1, v2
	v_lshl_add_u64 v[0:1], v[0:1], 2, s[0:1]
	v_cmp_gt_i32_e64 s[0:1], s12, v4
	s_ashr_i32 s15, s14, 31
	v_lshl_add_u64 v[0:1], s[14:15], 2, v[0:1]
	v_cndmask_b32_e64 v2, 0, v39, s[0:1]
	v_lshlrev_b32_e32 v2, 2, v2
	v_mov_b32_e32 v3, 0
	v_lshl_add_u64 v[4:5], v[0:1], 0, v[2:3]
	global_load_dwordx4 v[0:3], v[4:5], off nt
	s_cmp_lg_u64 s[10:11], 0
	s_mov_b32 s13, 0
	v_mov_b32_e32 v37, 1.0
	s_cselect_b64 s[14:15], -1, 0
	s_cmp_eq_u64 s[10:11], 0
	v_ashrrev_i32_e32 v33, 31, v32
	v_mov_b32_e32 v41, 1.0
	s_cbranch_scc1 .LBB0_57
	v_lshl_add_u64 v[6:7], v[32:33], 2, s[10:11]
	global_load_dword v41, v[6:7], off
.LBB0_57:
	s_lshl_b64 s[12:13], s[12:13], 6
	v_lshl_add_u64 v[8:9], v[4:5], 0, s[12:13]
	global_load_dwordx4 v[4:7], v[8:9], off nt
	v_cndmask_b32_e64 v10, 0, 1, s[14:15]
	v_cmp_ne_u32_e64 s[2:3], 1, v10
	s_andn2_b64 vcc, exec, s[14:15]
	s_cbranch_vccnz .LBB0_59
	v_lshl_add_u64 v[10:11], v[32:33], 2, s[10:11]
	global_load_dword v37, v[10:11], off offset:64
.LBB0_59:
	v_lshl_add_u64 v[12:13], v[8:9], 0, s[12:13]
	global_load_dwordx4 v[8:11], v[12:13], off nt
	v_mov_b32_e32 v40, 1.0
	s_and_b64 vcc, exec, s[2:3]
	v_mov_b32_e32 v42, 1.0
	s_cbranch_vccnz .LBB0_61
	v_lshl_add_u64 v[14:15], v[32:33], 2, s[10:11]
	global_load_dword v42, v[14:15], off offset:128
.LBB0_61:
	v_lshl_add_u64 v[16:17], v[12:13], 0, s[12:13]
	global_load_dwordx4 v[12:15], v[16:17], off nt
	s_and_b64 vcc, exec, s[2:3]
	s_cbranch_vccnz .LBB0_63
	v_lshl_add_u64 v[18:19], v[32:33], 2, s[10:11]
	global_load_dword v40, v[18:19], off offset:192
.LBB0_63:
	v_lshl_add_u64 v[20:21], v[16:17], 0, s[12:13]
	global_load_dwordx4 v[16:19], v[20:21], off nt
	v_mov_b32_e32 v36, 1.0
	s_and_b64 vcc, exec, s[2:3]
	v_mov_b32_e32 v38, 1.0
	s_cbranch_vccnz .LBB0_65
	v_lshl_add_u64 v[22:23], v[32:33], 2, s[10:11]
	global_load_dword v38, v[22:23], off offset:256
.LBB0_65:
	v_lshl_add_u64 v[24:25], v[20:21], 0, s[12:13]
	global_load_dwordx4 v[20:23], v[24:25], off nt
	s_and_b64 vcc, exec, s[2:3]
	s_cbranch_vccnz .LBB0_67
	v_lshl_add_u64 v[26:27], v[32:33], 2, s[10:11]
	global_load_dword v36, v[26:27], off offset:320
.LBB0_67:
	v_lshl_add_u64 v[28:29], v[24:25], 0, s[12:13]
	global_load_dwordx4 v[24:27], v[28:29], off nt
	v_mov_b32_e32 v43, 1.0
	s_and_b64 vcc, exec, s[2:3]
	v_mov_b32_e32 v34, 1.0
	s_cbranch_vccnz .LBB0_69
	v_lshl_add_u64 v[30:31], v[32:33], 2, s[10:11]
	global_load_dword v34, v[30:31], off offset:384
.LBB0_69:
	v_lshl_add_u64 v[28:29], v[28:29], 0, s[12:13]
	global_load_dwordx4 v[28:31], v[28:29], off nt
	s_and_b64 vcc, exec, s[2:3]
	s_cbranch_vccnz .LBB0_71
	v_lshl_add_u64 v[44:45], v[32:33], 2, s[10:11]
	global_load_dword v43, v[44:45], off offset:448

.LBB0_102:
	s_mul_i32 s2, s63, 0x10200
	s_add_i32 s66, s2, 0
	v_add3_u32 v37, s66, v47, v45
	v_pk_mul_f32 v[54:55], v[46:47], v[0:1] op_sel_hi:[0,1]
	v_pk_mul_f32 v[52:53], v[46:47], v[2:3] op_sel_hi:[0,1]
	ds_write2_b32 v37, v54, v55 offset1:1
	ds_write2_b32 v37, v52, v53 offset0:2 offset1:3
	v_add_u32_e32 v49, 0x2040, v37
	v_pk_mul_f32 v[54:55], v[44:45], v[4:5] op_sel_hi:[0,1]
	v_pk_mul_f32 v[52:53], v[44:45], v[6:7] op_sel_hi:[0,1]
	ds_write2_b32 v49, v54, v55 offset1:1
	v_add_u32_e32 v49, 0x2048, v37
	ds_write2_b32 v49, v52, v53 offset1:1
	v_add_u32_e32 v49, 0x4080, v37
	v_pk_mul_f32 v[54:55], v[42:43], v[8:9] op_sel_hi:[0,1]
	v_pk_mul_f32 v[52:53], v[42:43], v[10:11] op_sel_hi:[0,1]
	ds_write2_b32 v49, v54, v55 offset1:1
	v_add_u32_e32 v49, 0x4088, v37
	ds_write2_b32 v49, v52, v53 offset1:1
	v_add_u32_e32 v49, 0x60c0, v37
	v_pk_mul_f32 v[54:55], v[40:41], v[12:13] op_sel_hi:[0,1]
	v_pk_mul_f32 v[52:53], v[40:41], v[14:15] op_sel_hi:[0,1]
	ds_write2_b32 v49, v54, v55 offset1:1
	v_add_u32_e32 v49, 0x60c8, v37
	ds_write2_b32 v49, v52, v53 offset1:1
	v_add_u32_e32 v49, 0x8100, v37
	v_pk_mul_f32 v[54:55], v[38:39], v[16:17] op_sel_hi:[0,1]
	v_pk_mul_f32 v[52:53], v[38:39], v[18:19] op_sel_hi:[0,1]
	ds_write2_b32 v49, v54, v55 offset1:1
	v_add_u32_e32 v49, 0x8108, v37
	ds_write2_b32 v49, v52, v53 offset1:1
	v_add_u32_e32 v49, 0xa140, v37
	v_pk_mul_f32 v[54:55], v[36:37], v[20:21] op_sel_hi:[0,1]
	v_pk_mul_f32 v[52:53], v[36:37], v[22:23] op_sel_hi:[0,1]
	ds_write2_b32 v49, v54, v55 offset1:1
	v_add_u32_e32 v49, 0xa148, v37
	ds_write2_b32 v49, v52, v53 offset1:1
	v_add_u32_e32 v49, 0xc180, v37
	v_pk_mul_f32 v[54:55], v[34:35], v[24:25] op_sel_hi:[0,1]
	v_pk_mul_f32 v[52:53], v[34:35], v[26:27] op_sel_hi:[0,1]
	ds_write2_b32 v49, v54, v55 offset1:1
	v_add_u32_e32 v49, 0xc188, v37
	ds_write2_b32 v49, v52, v53 offset1:1
	v_add_u32_e32 v49, 0xe1c0, v37
	v_pk_mul_f32 v[52:53], v[48:49], v[30:31] op_sel_hi:[0,1]
	v_pk_mul_f32 v[54:55], v[48:49], v[28:29] op_sel_hi:[0,1]
	v_add_u32_e32 v37, 0xe1c8, v37
	s_andn2_b64 vcc, exec, s[0:1]
	ds_write2_b32 v49, v54, v55 offset1:1
	ds_write2_b32 v37, v52, v53 offset1:1
	s_cbranch_vccnz .LBB0_74
	v_add_u32_e32 v0, s4, v32
	v_add_u32_e32 v2, s10, v39
	v_mad_i64_i32 v[0:1], s[0:1], s84, v0, 0
	v_lshl_add_u64 v[0:1], v[0:1], 2, s[16:17]
	s_ashr_i32 s11, s10, 31
	v_cmp_gt_i32_e64 s[0:1], s84, v2
	v_lshl_add_u64 v[0:1], s[10:11], 2, v[0:1]
	s_cmp_lg_u64 s[14:15], 0
	v_cndmask_b32_e64 v34, 0, v39, s[0:1]
	v_lshl_add_u64 v[4:5], v[34:35], 2, v[0:1]
	global_load_dwordx4 v[0:3], v[4:5], off nt
	v_mov_b32_e32 v44, 1.0
	s_cselect_b64 s[88:89], -1, 0
	s_cmp_eq_u64 s[14:15], 0
	v_lshl_add_u64 v[36:37], v[32:33], 2, s[14:15]
	v_mov_b32_e32 v46, 1.0
	s_cbranch_scc1 .LBB0_105
	global_load_dword v46, v[36:37], off
.LBB0_105:
	s_ashr_i32 s85, s84, 31
	s_lshl_b64 s[86:87], s[84:85], 6
	v_lshl_add_u64 v[8:9], v[4:5], 0, s[86:87]
	global_load_dwordx4 v[4:7], v[8:9], off nt
	v_cndmask_b32_e64 v10, 0, 1, s[88:89]
	v_cmp_ne_u32_e64 s[2:3], 1, v10
	s_andn2_b64 vcc, exec, s[88:89]
	s_cbranch_vccnz .LBB0_107
	global_load_dword v44, v[36:37], off offset:64
.LBB0_107:
	v_lshl_add_u64 v[12:13], v[8:9], 0, s[86:87]
	global_load_dwordx4 v[8:11], v[12:13], off nt
	v_mov_b32_e32 v40, 1.0
	s_and_b64 vcc, exec, s[2:3]
	v_mov_b32_e32 v42, 1.0
	s_cbranch_vccnz .LBB0_109
	global_load_dword v42, v[36:37], off offset:128
.LBB0_109:
	v_lshl_add_u64 v[16:17], v[12:13], 0, s[86:87]
	global_load_dwordx4 v[12:15], v[16:17], off nt
	s_and_b64 vcc, exec, s[2:3]
	s_cbranch_vccnz .LBB0_111
	global_load_dword v40, v[36:37], off offset:192
.LBB0_111:
	v_lshl_add_u64 v[20:21], v[16:17], 0, s[86:87]
	global_load_dwordx4 v[16:19], v[20:21], off nt
	v_mov_b32_e32 v38, 1.0
	s_and_b64 vcc, exec, s[2:3]
	v_mov_b32_e32 v48, 1.0
	s_cbranch_vccnz .LBB0_113
	global_load_dword v48, v[36:37], off offset:256
.LBB0_113:
	v_lshl_add_u64 v[24:25], v[20:21], 0, s[86:87]
	global_load_dwordx4 v[20:23], v[24:25], off nt
	s_and_b64 vcc, exec, s[2:3]
	s_cbranch_vccnz .LBB0_115
	global_load_dword v38, v[36:37], off offset:320
.LBB0_115:
	v_lshl_add_u64 v[28:29], v[24:25], 0, s[86:87]
	global_load_dwordx4 v[24:27], v[28:29], off nt
	v_mov_b32_e32 v78, 1.0
	s_and_b64 vcc, exec, s[2:3]
	v_mov_b32_e32 v34, 1.0
	s_cbranch_vccnz .LBB0_117
	global_load_dword v34, v[36:37], off offset:384
.LBB0_117:
	v_lshl_add_u64 v[28:29], v[28:29], 0, s[86:87]
	global_load_dwordx4 v[28:31], v[28:29], off nt
	s_and_b64 vcc, exec, s[2:3]
	s_cbranch_vccnz .LBB0_73
	global_load_dword v78, v[36:37], off offset:448
	s_branch .LBB0_73

.LBB0_786:
	v_and_b32_e32 v39, 0x7c, v0
	v_add_u32_e32 v0, s8, v32
	s_waitcnt lgkmcnt(0)
	v_or_b32_e32 v2, s12, v39
	v_mad_i64_i32 v[0:1], s[16:17], s2, v0, 0
	v_lshl_add_u64 v[0:1], v[0:1], 2, s[0:1]
	v_cmp_gt_u32_e64 s[0:1], s2, v2
	s_mov_b32 s13, 0
	v_lshl_add_u64 v[0:1], s[12:13], 2, v[0:1]
	v_cndmask_b32_e64 v2, 0, v39, s[0:1]
	v_lshlrev_b32_e32 v2, 2, v2
	v_mov_b32_e32 v3, 0
	v_lshl_add_u64 v[4:5], v[0:1], 0, v[2:3]
	global_load_dwordx4 v[0:3], v[4:5], off nt
	s_cmp_lg_u64 s[14:15], 0
	v_mov_b32_e32 v37, 1.0
	s_cselect_b64 s[16:17], -1, 0
	s_cmp_eq_u64 s[14:15], 0
	v_ashrrev_i32_e32 v33, 31, v32
	v_mov_b32_e32 v41, 1.0
	s_cbranch_scc1 .LBB0_788
	v_lshl_add_u64 v[6:7], v[32:33], 2, s[14:15]
	global_load_dword v41, v[6:7], off
.LBB0_788:
	s_lshl_b32 s12, s2, 6
	v_lshl_add_u64 v[8:9], v[4:5], 0, s[12:13]
	global_load_dwordx4 v[4:7], v[8:9], off nt
	v_cndmask_b32_e64 v10, 0, 1, s[16:17]
	v_cmp_ne_u32_e64 s[2:3], 1, v10
	s_andn2_b64 vcc, exec, s[16:17]
	s_cbranch_vccnz .LBB0_790
	v_lshl_add_u64 v[10:11], v[32:33], 2, s[14:15]
	global_load_dword v37, v[10:11], off offset:64
.LBB0_790:
	v_lshl_add_u64 v[12:13], v[8:9], 0, s[12:13]
	global_load_dwordx4 v[8:11], v[12:13], off nt
	v_mov_b32_e32 v40, 1.0
	s_and_b64 vcc, exec, s[2:3]
	v_mov_b32_e32 v42, 1.0
	s_cbranch_vccnz .LBB0_792
	v_lshl_add_u64 v[14:15], v[32:33], 2, s[14:15]
	global_load_dword v42, v[14:15], off offset:128
.LBB0_792:
	v_lshl_add_u64 v[16:17], v[12:13], 0, s[12:13]
	global_load_dwordx4 v[12:15], v[16:17], off nt
	s_and_b64 vcc, exec, s[2:3]
	s_cbranch_vccnz .LBB0_794
	v_lshl_add_u64 v[18:19], v[32:33], 2, s[14:15]
	global_load_dword v40, v[18:19], off offset:192
.LBB0_794:
	v_lshl_add_u64 v[20:21], v[16:17], 0, s[12:13]
	global_load_dwordx4 v[16:19], v[20:21], off nt
	v_mov_b32_e32 v36, 1.0
	s_and_b64 vcc, exec, s[2:3]
	v_mov_b32_e32 v38, 1.0
	s_cbranch_vccnz .LBB0_796
	v_lshl_add_u64 v[22:23], v[32:33], 2, s[14:15]
	global_load_dword v38, v[22:23], off offset:256
.LBB0_796:
	v_lshl_add_u64 v[24:25], v[20:21], 0, s[12:13]
	global_load_dwordx4 v[20:23], v[24:25], off nt
	s_and_b64 vcc, exec, s[2:3]
	s_cbranch_vccnz .LBB0_798
	v_lshl_add_u64 v[26:27], v[32:33], 2, s[14:15]
	global_load_dword v36, v[26:27], off offset:320
.LBB0_798:
	v_lshl_add_u64 v[28:29], v[24:25], 0, s[12:13]
	global_load_dwordx4 v[24:27], v[28:29], off nt
	v_mov_b32_e32 v43, 1.0
	s_and_b64 vcc, exec, s[2:3]
	v_mov_b32_e32 v34, 1.0
	s_cbranch_vccnz .LBB0_800
	v_lshl_add_u64 v[30:31], v[32:33], 2, s[14:15]
	global_load_dword v34, v[30:31], off offset:384
.LBB0_800:
	v_lshl_add_u64 v[28:29], v[28:29], 0, s[12:13]
	global_load_dwordx4 v[28:31], v[28:29], off nt
	s_and_b64 vcc, exec, s[2:3]
	s_cbranch_vccnz .LBB0_802
	v_lshl_add_u64 v[44:45], v[32:33], 2, s[14:15]
	global_load_dword v43, v[44:45], off offset:448

.LBB0_805:
	v_lshlrev_b32_e32 v37, 2, v41
	v_add3_u32 v37, s41, v43, v37
	s_ashr_i32 s9, s8, 31
	v_add_u32_e32 v49, 0x400, v37
	v_add_u32_e32 v76, 0x800, v37
	v_add_u32_e32 v77, 0xc00, v37
	s_waitcnt lgkmcnt(0)
	s_barrier
	s_lshl_b64 s[0:1], s[8:9], 1
	ds_read2_b32 v[56:57], v37 offset1:32
	ds_read2_b32 v[58:59], v37 offset0:129 offset1:161
	ds_read2_b32 v[60:61], v49 offset0:2 offset1:34
	ds_read2_b32 v[62:63], v49 offset0:131 offset1:163
	ds_read2_b32 v[64:65], v76 offset0:4 offset1:36
	ds_read2_b32 v[66:67], v76 offset0:133 offset1:165
	ds_read2_b32 v[68:69], v77 offset0:6 offset1:38
	ds_read2_b32 v[70:71], v77 offset0:135 offset1:167
	s_add_u32 s0, s6, s0
	s_addc_u32 s1, s7, s1
	v_mov_b32_e32 v51, v35
	v_lshl_add_u64 v[72:73], s[0:1], 0, v[50:51]
	v_add_u32_e32 v51, s29, v41
	v_mad_i64_i32 v[74:75], s[0:1], s28, v51, 0
	s_waitcnt lgkmcnt(6)
	v_cvt_pk_bf16_f32 v52, v56, v58
	s_waitcnt lgkmcnt(4)
	v_cvt_pk_bf16_f32 v53, v60, v62
	s_waitcnt lgkmcnt(2)
	v_cvt_pk_bf16_f32 v54, v64, v66
	s_waitcnt lgkmcnt(0)
	v_cvt_pk_bf16_f32 v55, v68, v70
	v_lshl_add_u64 v[74:75], v[74:75], 1, v[72:73]
	global_store_dwordx4 v[74:75], v[52:55], off nt
	v_add_u32_e32 v56, 32, v51
	s_xor_b32 s34, s34, 1
	v_cvt_pk_bf16_f32 v52, v57, v59
	v_cvt_pk_bf16_f32 v53, v61, v63
	v_cvt_pk_bf16_f32 v54, v65, v67
	v_cvt_pk_bf16_f32 v55, v69, v71
	ds_read2_b32 v[58:59], v37 offset0:64 offset1:96
	ds_read2_b32 v[60:61], v37 offset0:193 offset1:225
	ds_read2_b32 v[62:63], v49 offset0:66 offset1:98
	ds_read2_b32 v[64:65], v49 offset0:195 offset1:227
	ds_read2_b32 v[66:67], v76 offset0:68 offset1:100
	ds_read2_b32 v[68:69], v76 offset0:197 offset1:229
	ds_read2_b32 v[70:71], v77 offset0:70 offset1:102
	ds_read2_b32 v[74:75], v77 offset0:199 offset1:231
	v_mad_i64_i32 v[56:57], s[0:1], s28, v56, 0
	v_lshl_add_u64 v[56:57], v[56:57], 1, v[72:73]
	v_add_u32_e32 v37, 64, v51
	global_store_dwordx4 v[56:57], v[52:55], off nt
	v_mad_i64_i32 v[56:57], s[0:1], s28, v37, 0
	s_waitcnt lgkmcnt(6)
	v_cvt_pk_bf16_f32 v52, v58, v60
	s_waitcnt lgkmcnt(4)
	v_cvt_pk_bf16_f32 v53, v62, v64
	s_waitcnt lgkmcnt(2)
	v_cvt_pk_bf16_f32 v54, v66, v68
	s_waitcnt lgkmcnt(0)
	v_cvt_pk_bf16_f32 v55, v70, v74
	v_lshl_add_u64 v[56:57], v[56:57], 1, v[72:73]
	v_add_u32_e32 v37, 0x60, v51
	global_store_dwordx4 v[56:57], v[52:55], off nt
	v_mad_i64_i32 v[56:57], s[0:1], s28, v37, 0
	s_addk_i32 s30, 0xbe
	s_addk_i32 s31, 0x5f00
	s_addk_i32 s33, 0x5f0
	v_cvt_pk_bf16_f32 v52, v59, v61
	v_cvt_pk_bf16_f32 v53, v63, v65
	v_cvt_pk_bf16_f32 v54, v67, v69
	v_cvt_pk_bf16_f32 v55, v71, v75
	v_lshl_add_u64 v[56:57], v[56:57], 1, v[72:73]
	s_cmpk_lt_i32 s40, 0xd52
	s_mov_b32 s29, s39
	s_mov_b64 s[6:7], s[22:23]
	s_mov_b32 s28, s38
	s_mov_b32 s8, s35
	global_store_dwordx4 v[56:57], v[52:55], off nt
	s_cbranch_scc0 .LBB0_829
	s_waitcnt vmcnt(5)
	v_cndmask_b32_e64 v34, 0, v34, s[100:101]
	v_cndmask_b32_e64 v36, 0, v38, s[100:101]
	v_cndmask_b32_e64 v38, 0, v48, s[100:101]
	v_cndmask_b32_e64 v40, 0, v40, s[100:101]
	v_cndmask_b32_e64 v42, 0, v42, s[100:101]
	v_cndmask_b32_e64 v44, 0, v44, s[100:101]
	v_cndmask_b32_e64 v46, 0, v46, s[100:101]
	s_waitcnt vmcnt(4)
	v_cndmask_b32_e64 v48, 0, v78, s[100:101]

.LBB0_812:
	s_mul_i32 s2, s34, 0x10200
	s_add_i32 s41, s2, 0
	v_add3_u32 v37, s41, v47, v45
	v_pk_mul_f32 v[54:55], v[46:47], v[0:1] op_sel_hi:[0,1]
	v_pk_mul_f32 v[52:53], v[46:47], v[2:3] op_sel_hi:[0,1]
	ds_write2_b32 v37, v54, v55 offset1:1
	ds_write2_b32 v37, v52, v53 offset0:2 offset1:3
	v_add_u32_e32 v49, 0x2040, v37
	v_pk_mul_f32 v[54:55], v[44:45], v[4:5] op_sel_hi:[0,1]
	v_pk_mul_f32 v[52:53], v[44:45], v[6:7] op_sel_hi:[0,1]
	ds_write2_b32 v49, v54, v55 offset1:1
	v_add_u32_e32 v49, 0x2048, v37
	ds_write2_b32 v49, v52, v53 offset1:1
	v_add_u32_e32 v49, 0x4080, v37
	v_pk_mul_f32 v[54:55], v[42:43], v[8:9] op_sel_hi:[0,1]
	v_pk_mul_f32 v[52:53], v[42:43], v[10:11] op_sel_hi:[0,1]
	ds_write2_b32 v49, v54, v55 offset1:1
	v_add_u32_e32 v49, 0x4088, v37
	ds_write2_b32 v49, v52, v53 offset1:1
	v_add_u32_e32 v49, 0x60c0, v37
	v_pk_mul_f32 v[54:55], v[40:41], v[12:13] op_sel_hi:[0,1]
	v_pk_mul_f32 v[52:53], v[40:41], v[14:15] op_sel_hi:[0,1]
	ds_write2_b32 v49, v54, v55 offset1:1
	v_add_u32_e32 v49, 0x60c8, v37
	ds_write2_b32 v49, v52, v53 offset1:1
	v_add_u32_e32 v49, 0x8100, v37
	v_pk_mul_f32 v[54:55], v[38:39], v[16:17] op_sel_hi:[0,1]
	v_pk_mul_f32 v[52:53], v[38:39], v[18:19] op_sel_hi:[0,1]
	ds_write2_b32 v49, v54, v55 offset1:1
	v_add_u32_e32 v49, 0x8108, v37
	ds_write2_b32 v49, v52, v53 offset1:1
	v_add_u32_e32 v49, 0xa140, v37
	v_pk_mul_f32 v[54:55], v[36:37], v[20:21] op_sel_hi:[0,1]
	v_pk_mul_f32 v[52:53], v[36:37], v[22:23] op_sel_hi:[0,1]
	ds_write2_b32 v49, v54, v55 offset1:1
	v_add_u32_e32 v49, 0xa148, v37
	ds_write2_b32 v49, v52, v53 offset1:1
	v_add_u32_e32 v49, 0xc180, v37
	v_pk_mul_f32 v[54:55], v[34:35], v[24:25] op_sel_hi:[0,1]
	v_pk_mul_f32 v[52:53], v[34:35], v[26:27] op_sel_hi:[0,1]
	ds_write2_b32 v49, v54, v55 offset1:1
	v_add_u32_e32 v49, 0xc188, v37
	ds_write2_b32 v49, v52, v53 offset1:1
	v_add_u32_e32 v49, 0xe1c0, v37
	v_pk_mul_f32 v[52:53], v[48:49], v[30:31] op_sel_hi:[0,1]
	v_pk_mul_f32 v[54:55], v[48:49], v[28:29] op_sel_hi:[0,1]
	v_add_u32_e32 v37, 0xe1c8, v37
	s_andn2_b64 vcc, exec, s[0:1]
	ds_write2_b32 v49, v54, v55 offset1:1
	ds_write2_b32 v37, v52, v53 offset1:1
	s_cbranch_vccnz .LBB0_805
	v_add_u32_e32 v0, s35, v32
	v_add_u32_e32 v2, s16, v39
	v_mad_i64_i32 v[0:1], s[0:1], s20, v0, 0
	v_lshl_add_u64 v[0:1], v[0:1], 2, s[14:15]
	s_ashr_i32 s17, s16, 31
	v_cmp_gt_i32_e64 s[0:1], s20, v2
	v_lshl_add_u64 v[0:1], s[16:17], 2, v[0:1]
	s_cmp_lg_u64 s[18:19], 0
	v_cndmask_b32_e64 v34, 0, v39, s[0:1]
	v_lshl_add_u64 v[4:5], v[34:35], 2, v[0:1]
	global_load_dwordx4 v[0:3], v[4:5], off nt
	v_mov_b32_e32 v44, 1.0
	s_cselect_b64 s[26:27], -1, 0
	s_cmp_eq_u64 s[18:19], 0
	v_lshl_add_u64 v[36:37], v[32:33], 2, s[18:19]
	v_mov_b32_e32 v46, 1.0
	s_cbranch_scc1 .LBB0_815
	global_load_dword v46, v[36:37], off
.LBB0_815:
	s_ashr_i32 s21, s20, 31
	s_lshl_b64 s[24:25], s[20:21], 6
	v_lshl_add_u64 v[8:9], v[4:5], 0, s[24:25]
	global_load_dwordx4 v[4:7], v[8:9], off nt
	v_cndmask_b32_e64 v10, 0, 1, s[26:27]
	v_cmp_ne_u32_e64 s[2:3], 1, v10
	s_andn2_b64 vcc, exec, s[26:27]
	s_cbranch_vccnz .LBB0_817
	global_load_dword v44, v[36:37], off offset:64
.LBB0_817:
	v_lshl_add_u64 v[12:13], v[8:9], 0, s[24:25]
	global_load_dwordx4 v[8:11], v[12:13], off nt
	v_mov_b32_e32 v40, 1.0
	s_and_b64 vcc, exec, s[2:3]
	v_mov_b32_e32 v42, 1.0
	s_cbranch_vccnz .LBB0_819
	global_load_dword v42, v[36:37], off offset:128
.LBB0_819:
	v_lshl_add_u64 v[16:17], v[12:13], 0, s[24:25]
	global_load_dwordx4 v[12:15], v[16:17], off nt
	s_and_b64 vcc, exec, s[2:3]
	s_cbranch_vccnz .LBB0_821
	global_load_dword v40, v[36:37], off offset:192
.LBB0_821:
	v_lshl_add_u64 v[20:21], v[16:17], 0, s[24:25]
	global_load_dwordx4 v[16:19], v[20:21], off nt
	v_mov_b32_e32 v38, 1.0
	s_and_b64 vcc, exec, s[2:3]
	v_mov_b32_e32 v48, 1.0
	s_cbranch_vccnz .LBB0_823
	global_load_dword v48, v[36:37], off offset:256
.LBB0_823:
	v_lshl_add_u64 v[24:25], v[20:21], 0, s[24:25]
	global_load_dwordx4 v[20:23], v[24:25], off nt
	s_and_b64 vcc, exec, s[2:3]
	s_cbranch_vccnz .LBB0_825
	global_load_dword v38, v[36:37], off offset:320
.LBB0_825:
	v_lshl_add_u64 v[28:29], v[24:25], 0, s[24:25]
	global_load_dwordx4 v[24:27], v[28:29], off nt
	v_mov_b32_e32 v78, 1.0
	s_and_b64 vcc, exec, s[2:3]
	v_mov_b32_e32 v34, 1.0
	s_cbranch_vccnz .LBB0_827
	global_load_dword v34, v[36:37], off offset:384
.LBB0_827:
	v_lshl_add_u64 v[28:29], v[28:29], 0, s[24:25]
	global_load_dwordx4 v[28:31], v[28:29], off nt
	s_and_b64 vcc, exec, s[2:3]
	s_cbranch_vccnz .LBB0_804
	global_load_dword v78, v[36:37], off offset:448
	s_branch .LBB0_804
